# HGRN consumer loop: unrolled 4 blocks, LDS reads hoisted and prefetched, scalar-base stores
# speedup vs baseline: 1.0081x; 1.0081x over previous
.LBB0_146:
	v_mov_b32_e32 v36, v188
	s_nop 0
	v_readfirstlane_b32 s0, v36
	s_ashr_i32 s12, s0, 6
	s_lshl_b32 s0, s3, 6
	s_and_b32 s11, s0, 0x780
	s_and_b32 s10, s0, 64
	s_cmp_lt_u32 s3, 64
	s_cselect_b64 s[36:37], -1, 0
	s_lshl_b32 s0, s3, 8
	s_and_b32 s4, s0, 0x2000
	v_and_b32_e32 v110, 15, v36
	v_lshrrev_b32_e32 v104, 4, v36
	v_bfe_u32 v106, v36, 4, 2
	s_cmp_lt_i32 s12, 4
	s_mov_b64 s[0:1], -1
	s_cbranch_scc0 .LBB0_153
	s_and_b64 s[14:15], s[36:37], exec
	s_cselect_b32 s1, 0, 0x4000000
	s_add_u32 s1, s88, s1
	s_addc_u32 s13, s89, 0
	s_lshl_b32 s14, s11, 1
	s_add_u32 s1, s1, s14
	s_addc_u32 s13, s13, 0
	s_lshl_b32 s14, s10, 1
	s_add_u32 s1, s1, s14
	s_addc_u32 s13, s13, 0
	s_lshl_b32 s14, s12, 4
	s_ashr_i32 s15, s14, 31
	s_lshl_b64 s[14:15], s[14:15], 1
	s_waitcnt lgkmcnt(0)
	v_lshlrev_b32_e32 v2, 3, v106
	s_add_u32 s14, s1, s14
	s_movk_i32 s1, 0x90
	v_mad_u32_u24 v3, v110, s1, v2
	v_readlane_b32 s1, v247, 63
	s_mulk_i32 s12, 0x900
	s_addc_u32 s15, s13, s15
	v_add_u32_e32 v40, s1, v3
	s_add_i32 s1, s12, 0
	v_cmp_gt_u32_e32 vcc, 2, v106
	s_add_i32 s1, s1, 0xd000
	v_add_u32_e32 v41, s1, v3
	v_cndmask_b32_e64 v0, v195, 0, vcc
	s_movk_i32 s1, 0x110
	v_lshlrev_b32_e32 v1, 3, v104
	v_lshlrev_b32_e32 v96, 1, v110
	v_mad_u32_u24 v0, v110, s1, v0
	v_lshl_add_u64 v[32:33], s[14:15], 0, v[96:97]
	v_mul_u32_u24_e32 v3, 0x110, v110
	v_and_or_b32 v0, v1, 8, v0
	v_readlane_b32 s1, v248, 0
	v_mov_b32_e32 v96, v97
	v_lshlrev_b32_e32 v37, 2, v106
	v_add_u32_e32 v42, s1, v0
	v_add3_u32 v43, v3, v2, 0
	v_mov_b32_e32 v98, v97
	s_waitcnt vmcnt(0)
	v_mov_b32_e32 v99, v97
	v_mov_b64_e32 v[0:1], v[96:97]
	v_mov_b64_e32 v[4:5], v[96:97]
	v_mov_b64_e32 v[8:9], v[96:97]
	v_mov_b64_e32 v[12:13], v[96:97]
	v_mov_b64_e32 v[16:17], v[96:97]
	v_mov_b64_e32 v[20:21], v[96:97]
	v_mov_b64_e32 v[24:25], v[96:97]
	v_mov_b64_e32 v[28:29], v[96:97]
	v_mov_b64_e32 v[2:3], v[98:99]
	v_mov_b64_e32 v[6:7], v[98:99]
	v_mov_b64_e32 v[10:11], v[98:99]
	v_mov_b64_e32 v[14:15], v[98:99]
	v_mov_b64_e32 v[18:19], v[98:99]
	v_mov_b64_e32 v[22:23], v[98:99]
	v_mov_b64_e32 v[26:27], v[98:99]
	v_mov_b64_e32 v[30:31], v[98:99]
	v_lshl_add_u32 v38, v106, 4, s73
	v_xor_b32_e32 v39, 0x203c, v37
	s_lshl_b32 s1, s4, 12
	s_add_u32 s14, s14, s1
	s_addc_u32 s15, s15, 0
	s_mov_b32 s13, 0x10000
	s_cmp_lt_u32 s3, 64
	s_cselect_b32 s13, s13, 0xffff0000
	s_ashr_i32 s1, s13, 4
	v_add_u32_e32 v58, 0xffffffc3, v39
	v_cndmask_b32_e64 v58, v58, v37, s[36:37]
	v_lshlrev_b32_e32 v58, 12, v58
	v_lshl_add_u32 v160, v110, 1, v58
	v_add_u32_e32 v161, s1, v160
	v_add_u32_e32 v162, s1, v161
	v_add_u32_e32 v163, s1, v162
	s_mov_b32 s0, 1
	s_barrier
.Lhc_stage:
	s_bitcmp1_b32 s0, 0
	s_cselect_b32 s12, 0, 0xfc00
	v_add_u32_e32 v45, s12, v42
	v_add_u32_e32 v46, s12, v41
	v_add_u32_e32 v44, s12, v43
	v_add_u32_e32 v49, s12, v38
	v_add_u32_e32 v47, s12, v40
	ds_read_b64 v[62:63], v45 offset:0
	ds_read_b64 v[34:35], v46 offset:0
	ds_read2_b64 v[68:71], v44 offset0:0 offset1:4
	ds_read2_b64 v[72:75], v44 offset0:8 offset1:12
	ds_read2_b64 v[76:79], v44 offset0:16 offset1:20
	ds_read2_b64 v[80:83], v44 offset0:24 offset1:28
	v_add_u32_e32 v164, 0x1100, v44
	v_add_u32_e32 v165, 0x2200, v44
	v_add_u32_e32 v166, 0x3300, v44
	ds_read_b128 v[112:115], v49 offset:0
	ds_read_b64 v[144:145], v47 offset:0
	ds_read_b128 v[116:119], v49 offset:64
	ds_read_b64 v[146:147], v47 offset:2304
	ds_read_b128 v[120:123], v49 offset:128
	ds_read_b64 v[148:149], v47 offset:4608
	ds_read_b128 v[124:127], v49 offset:192
	ds_read_b64 v[150:151], v47 offset:6912
	v_cvt_pk_bf16_f32 v84, v28, v29
	v_cvt_pk_bf16_f32 v85, v30, v31
	v_cvt_pk_bf16_f32 v86, v24, v25
	v_cvt_pk_bf16_f32 v87, v26, v27
	s_waitcnt lgkmcnt(8)
	v_mfma_f32_16x16x16_bf16 v[50:53], v[62:63], v[34:35], 0
	v_cvt_pk_bf16_f32 v88, v20, v21
	v_cvt_pk_bf16_f32 v89, v22, v23
	v_mfma_f32_16x16x16_bf16 v[50:53], v[68:69], v[84:85], v[50:53]
	v_mfma_f32_16x16x16_bf16 v[54:57], v[70:71], v[86:87], 0
	v_cvt_pk_bf16_f32 v90, v16, v17
	v_cvt_pk_bf16_f32 v91, v18, v19
	ds_read_b128 v[128:131], v49 offset:256
	ds_read_b64 v[152:153], v47 offset:9216
	v_mfma_f32_16x16x16_bf16 v[50:53], v[72:73], v[88:89], v[50:53]
	v_cvt_pk_bf16_f32 v92, v12, v13
	v_cvt_pk_bf16_f32 v93, v14, v15
	ds_read_b128 v[132:135], v49 offset:320
	ds_read_b64 v[154:155], v47 offset:11520
	v_mfma_f32_16x16x16_bf16 v[54:57], v[74:75], v[90:91], v[54:57]
	v_cvt_pk_bf16_f32 v94, v8, v9
	v_cvt_pk_bf16_f32 v95, v10, v11
	ds_read_b128 v[136:139], v49 offset:384
	ds_read_b64 v[156:157], v47 offset:13824
	v_mfma_f32_16x16x16_bf16 v[50:53], v[76:77], v[92:93], v[50:53]
	v_cvt_pk_bf16_f32 v100, v4, v5
	v_cvt_pk_bf16_f32 v101, v6, v7
	ds_read_b128 v[140:143], v49 offset:448
	ds_read_b64 v[158:159], v47 offset:16128
	v_mfma_f32_16x16x16_bf16 v[54:57], v[78:79], v[94:95], v[54:57]
	v_cvt_pk_bf16_f32 v102, v0, v1
	v_cvt_pk_bf16_f32 v103, v2, v3
	v_mfma_f32_16x16x16_bf16 v[50:53], v[80:81], v[100:101], v[50:53]
	ds_read_b64 v[62:63], v45 offset:4352
	v_mfma_f32_16x16x16_bf16 v[54:57], v[82:83], v[102:103], v[54:57]
	ds_read_b64 v[60:61], v46 offset:32
	ds_read2_b64 v[68:71], v164 offset0:0 offset1:4
	ds_read2_b64 v[72:75], v164 offset0:8 offset1:12
	ds_read2_b64 v[76:79], v164 offset0:16 offset1:20
	ds_read2_b64 v[80:83], v164 offset0:24 offset1:28
	s_nop 2
	v_pk_add_f32 v[52:53], v[52:53], v[56:57]
	v_pk_add_f32 v[50:51], v[50:51], v[54:55]
	v_cvt_pk_bf16_f32 v59, v52, v53
	v_cvt_pk_bf16_f32 v58, v50, v51
	global_store_short v160, v58, s[14:15]
	global_store_short_d16_hi v161, v58, s[14:15]
	global_store_short v162, v59, s[14:15]
	global_store_short_d16_hi v163, v59, s[14:15]
	v_add_u32_e32 v160, s13, v160
	v_add_u32_e32 v161, s13, v161
	v_add_u32_e32 v162, s13, v162
	v_add_u32_e32 v163, s13, v163
	s_waitcnt lgkmcnt(6)
	v_pk_mul_f32 v[30:31], v[30:31], v[114:115]
	v_pk_mul_f32 v[28:29], v[28:29], v[112:113]
	v_pk_mul_f32 v[26:27], v[26:27], v[118:119]
	v_pk_mul_f32 v[24:25], v[24:25], v[116:117]
	v_mfma_f32_16x16x16_bf16 v[28:31], v[144:145], v[34:35], v[28:31]
	v_pk_mul_f32 v[22:23], v[22:23], v[122:123]
	v_pk_mul_f32 v[20:21], v[20:21], v[120:121]
	v_mfma_f32_16x16x16_bf16 v[24:27], v[146:147], v[34:35], v[24:27]
	v_pk_mul_f32 v[18:19], v[18:19], v[126:127]
	v_pk_mul_f32 v[16:17], v[16:17], v[124:125]
	v_mfma_f32_16x16x16_bf16 v[20:23], v[148:149], v[34:35], v[20:23]
	v_pk_mul_f32 v[14:15], v[14:15], v[130:131]
	v_pk_mul_f32 v[12:13], v[12:13], v[128:129]
	v_mfma_f32_16x16x16_bf16 v[16:19], v[150:151], v[34:35], v[16:19]
	v_pk_mul_f32 v[10:11], v[10:11], v[134:135]
	v_pk_mul_f32 v[8:9], v[8:9], v[132:133]
	v_mfma_f32_16x16x16_bf16 v[12:15], v[152:153], v[34:35], v[12:15]
	v_pk_mul_f32 v[6:7], v[6:7], v[138:139]
	v_pk_mul_f32 v[4:5], v[4:5], v[136:137]
	v_mfma_f32_16x16x16_bf16 v[8:11], v[154:155], v[34:35], v[8:11]
	v_pk_mul_f32 v[2:3], v[2:3], v[142:143]
	v_pk_mul_f32 v[0:1], v[0:1], v[140:141]
	v_mfma_f32_16x16x16_bf16 v[4:7], v[156:157], v[34:35], v[4:7]
	s_nop 1
	v_mfma_f32_16x16x16_bf16 v[0:3], v[158:159], v[34:35], v[0:3]
	ds_read_b128 v[112:115], v49 offset:512
	ds_read_b64 v[144:145], v47 offset:32
	ds_read_b128 v[116:119], v49 offset:576
	ds_read_b64 v[146:147], v47 offset:2336
	ds_read_b128 v[120:123], v49 offset:640
	ds_read_b64 v[148:149], v47 offset:4640
	ds_read_b128 v[124:127], v49 offset:704
	ds_read_b64 v[150:151], v47 offset:6944
	v_cvt_pk_bf16_f32 v84, v28, v29
	v_cvt_pk_bf16_f32 v85, v30, v31
	v_cvt_pk_bf16_f32 v86, v24, v25
	v_cvt_pk_bf16_f32 v87, v26, v27
	s_waitcnt lgkmcnt(8)
	v_mfma_f32_16x16x16_bf16 v[50:53], v[62:63], v[60:61], 0
	v_cvt_pk_bf16_f32 v88, v20, v21
	v_cvt_pk_bf16_f32 v89, v22, v23
	v_mfma_f32_16x16x16_bf16 v[50:53], v[68:69], v[84:85], v[50:53]
	v_mfma_f32_16x16x16_bf16 v[54:57], v[70:71], v[86:87], 0
	v_cvt_pk_bf16_f32 v90, v16, v17
	v_cvt_pk_bf16_f32 v91, v18, v19
	ds_read_b128 v[128:131], v49 offset:768
	ds_read_b64 v[152:153], v47 offset:9248
	v_mfma_f32_16x16x16_bf16 v[50:53], v[72:73], v[88:89], v[50:53]
	v_cvt_pk_bf16_f32 v92, v12, v13
	v_cvt_pk_bf16_f32 v93, v14, v15
	ds_read_b128 v[132:135], v49 offset:832
	ds_read_b64 v[154:155], v47 offset:11552
	v_mfma_f32_16x16x16_bf16 v[54:57], v[74:75], v[90:91], v[54:57]
	v_cvt_pk_bf16_f32 v94, v8, v9
	v_cvt_pk_bf16_f32 v95, v10, v11
	ds_read_b128 v[136:139], v49 offset:896
	ds_read_b64 v[156:157], v47 offset:13856
	v_mfma_f32_16x16x16_bf16 v[50:53], v[76:77], v[92:93], v[50:53]
	v_cvt_pk_bf16_f32 v100, v4, v5
	v_cvt_pk_bf16_f32 v101, v6, v7
	ds_read_b128 v[140:143], v49 offset:960
	ds_read_b64 v[158:159], v47 offset:16160
	v_mfma_f32_16x16x16_bf16 v[54:57], v[78:79], v[94:95], v[54:57]
	v_cvt_pk_bf16_f32 v102, v0, v1
	v_cvt_pk_bf16_f32 v103, v2, v3
	v_mfma_f32_16x16x16_bf16 v[50:53], v[80:81], v[100:101], v[50:53]
	ds_read_b64 v[62:63], v45 offset:8704
	v_mfma_f32_16x16x16_bf16 v[54:57], v[82:83], v[102:103], v[54:57]
	ds_read_b64 v[34:35], v46 offset:64
	ds_read2_b64 v[68:71], v165 offset0:0 offset1:4
	ds_read2_b64 v[72:75], v165 offset0:8 offset1:12
	ds_read2_b64 v[76:79], v165 offset0:16 offset1:20
	ds_read2_b64 v[80:83], v165 offset0:24 offset1:28
	s_nop 2
	v_pk_add_f32 v[52:53], v[52:53], v[56:57]
	v_pk_add_f32 v[50:51], v[50:51], v[54:55]
	v_cvt_pk_bf16_f32 v59, v52, v53
	v_cvt_pk_bf16_f32 v58, v50, v51
	global_store_short v160, v58, s[14:15]
	global_store_short_d16_hi v161, v58, s[14:15]
	global_store_short v162, v59, s[14:15]
	global_store_short_d16_hi v163, v59, s[14:15]
	v_add_u32_e32 v160, s13, v160
	v_add_u32_e32 v161, s13, v161
	v_add_u32_e32 v162, s13, v162
	v_add_u32_e32 v163, s13, v163
	s_waitcnt lgkmcnt(6)
	v_pk_mul_f32 v[30:31], v[30:31], v[114:115]
	v_pk_mul_f32 v[28:29], v[28:29], v[112:113]
	v_pk_mul_f32 v[26:27], v[26:27], v[118:119]
	v_pk_mul_f32 v[24:25], v[24:25], v[116:117]
	v_mfma_f32_16x16x16_bf16 v[28:31], v[144:145], v[60:61], v[28:31]
	v_pk_mul_f32 v[22:23], v[22:23], v[122:123]
	v_pk_mul_f32 v[20:21], v[20:21], v[120:121]
	v_mfma_f32_16x16x16_bf16 v[24:27], v[146:147], v[60:61], v[24:27]
	v_pk_mul_f32 v[18:19], v[18:19], v[126:127]
	v_pk_mul_f32 v[16:17], v[16:17], v[124:125]
	v_mfma_f32_16x16x16_bf16 v[20:23], v[148:149], v[60:61], v[20:23]
	v_pk_mul_f32 v[14:15], v[14:15], v[130:131]
	v_pk_mul_f32 v[12:13], v[12:13], v[128:129]
	v_mfma_f32_16x16x16_bf16 v[16:19], v[150:151], v[60:61], v[16:19]
	v_pk_mul_f32 v[10:11], v[10:11], v[134:135]
	v_pk_mul_f32 v[8:9], v[8:9], v[132:133]
	v_mfma_f32_16x16x16_bf16 v[12:15], v[152:153], v[60:61], v[12:15]
	v_pk_mul_f32 v[6:7], v[6:7], v[138:139]
	v_pk_mul_f32 v[4:5], v[4:5], v[136:137]
	v_mfma_f32_16x16x16_bf16 v[8:11], v[154:155], v[60:61], v[8:11]
	v_pk_mul_f32 v[2:3], v[2:3], v[142:143]
	v_pk_mul_f32 v[0:1], v[0:1], v[140:141]
	v_mfma_f32_16x16x16_bf16 v[4:7], v[156:157], v[60:61], v[4:7]
	s_nop 1
	v_mfma_f32_16x16x16_bf16 v[0:3], v[158:159], v[60:61], v[0:3]
	ds_read_b128 v[112:115], v49 offset:1024
	ds_read_b64 v[144:145], v47 offset:64
	ds_read_b128 v[116:119], v49 offset:1088
	ds_read_b64 v[146:147], v47 offset:2368
	ds_read_b128 v[120:123], v49 offset:1152
	ds_read_b64 v[148:149], v47 offset:4672
	ds_read_b128 v[124:127], v49 offset:1216
	ds_read_b64 v[150:151], v47 offset:6976
	v_cvt_pk_bf16_f32 v84, v28, v29
	v_cvt_pk_bf16_f32 v85, v30, v31
	v_cvt_pk_bf16_f32 v86, v24, v25
	v_cvt_pk_bf16_f32 v87, v26, v27
	s_waitcnt lgkmcnt(8)
	v_mfma_f32_16x16x16_bf16 v[50:53], v[62:63], v[34:35], 0
	v_cvt_pk_bf16_f32 v88, v20, v21
	v_cvt_pk_bf16_f32 v89, v22, v23
	v_mfma_f32_16x16x16_bf16 v[50:53], v[68:69], v[84:85], v[50:53]
	v_mfma_f32_16x16x16_bf16 v[54:57], v[70:71], v[86:87], 0
	v_cvt_pk_bf16_f32 v90, v16, v17
	v_cvt_pk_bf16_f32 v91, v18, v19
	ds_read_b128 v[128:131], v49 offset:1280
	ds_read_b64 v[152:153], v47 offset:9280
	v_mfma_f32_16x16x16_bf16 v[50:53], v[72:73], v[88:89], v[50:53]
	v_cvt_pk_bf16_f32 v92, v12, v13
	v_cvt_pk_bf16_f32 v93, v14, v15
	ds_read_b128 v[132:135], v49 offset:1344
	ds_read_b64 v[154:155], v47 offset:11584
	v_mfma_f32_16x16x16_bf16 v[54:57], v[74:75], v[90:91], v[54:57]
	v_cvt_pk_bf16_f32 v94, v8, v9
	v_cvt_pk_bf16_f32 v95, v10, v11
	ds_read_b128 v[136:139], v49 offset:1408
	ds_read_b64 v[156:157], v47 offset:13888
	v_mfma_f32_16x16x16_bf16 v[50:53], v[76:77], v[92:93], v[50:53]
	v_cvt_pk_bf16_f32 v100, v4, v5
	v_cvt_pk_bf16_f32 v101, v6, v7
	ds_read_b128 v[140:143], v49 offset:1472
	ds_read_b64 v[158:159], v47 offset:16192
	v_mfma_f32_16x16x16_bf16 v[54:57], v[78:79], v[94:95], v[54:57]
	v_cvt_pk_bf16_f32 v102, v0, v1
	v_cvt_pk_bf16_f32 v103, v2, v3
	v_mfma_f32_16x16x16_bf16 v[50:53], v[80:81], v[100:101], v[50:53]
	ds_read_b64 v[62:63], v45 offset:13056
	v_mfma_f32_16x16x16_bf16 v[54:57], v[82:83], v[102:103], v[54:57]
	ds_read_b64 v[60:61], v46 offset:96
	ds_read2_b64 v[68:71], v166 offset0:0 offset1:4
	ds_read2_b64 v[72:75], v166 offset0:8 offset1:12
	ds_read2_b64 v[76:79], v166 offset0:16 offset1:20
	ds_read2_b64 v[80:83], v166 offset0:24 offset1:28
	s_nop 2
	v_pk_add_f32 v[52:53], v[52:53], v[56:57]
	v_pk_add_f32 v[50:51], v[50:51], v[54:55]
	v_cvt_pk_bf16_f32 v59, v52, v53
	v_cvt_pk_bf16_f32 v58, v50, v51
	global_store_short v160, v58, s[14:15]
	global_store_short_d16_hi v161, v58, s[14:15]
	global_store_short v162, v59, s[14:15]
	global_store_short_d16_hi v163, v59, s[14:15]
	v_add_u32_e32 v160, s13, v160
	v_add_u32_e32 v161, s13, v161
	v_add_u32_e32 v162, s13, v162
	v_add_u32_e32 v163, s13, v163
	s_waitcnt lgkmcnt(6)
	v_pk_mul_f32 v[30:31], v[30:31], v[114:115]
	v_pk_mul_f32 v[28:29], v[28:29], v[112:113]
	v_pk_mul_f32 v[26:27], v[26:27], v[118:119]
	v_pk_mul_f32 v[24:25], v[24:25], v[116:117]
	v_mfma_f32_16x16x16_bf16 v[28:31], v[144:145], v[34:35], v[28:31]
	v_pk_mul_f32 v[22:23], v[22:23], v[122:123]
	v_pk_mul_f32 v[20:21], v[20:21], v[120:121]
	v_mfma_f32_16x16x16_bf16 v[24:27], v[146:147], v[34:35], v[24:27]
	v_pk_mul_f32 v[18:19], v[18:19], v[126:127]
	v_pk_mul_f32 v[16:17], v[16:17], v[124:125]
	v_mfma_f32_16x16x16_bf16 v[20:23], v[148:149], v[34:35], v[20:23]
	v_pk_mul_f32 v[14:15], v[14:15], v[130:131]
	v_pk_mul_f32 v[12:13], v[12:13], v[128:129]
	v_mfma_f32_16x16x16_bf16 v[16:19], v[150:151], v[34:35], v[16:19]
	v_pk_mul_f32 v[10:11], v[10:11], v[134:135]
	v_pk_mul_f32 v[8:9], v[8:9], v[132:133]
	v_mfma_f32_16x16x16_bf16 v[12:15], v[152:153], v[34:35], v[12:15]
	v_pk_mul_f32 v[6:7], v[6:7], v[138:139]
	v_pk_mul_f32 v[4:5], v[4:5], v[136:137]
	v_mfma_f32_16x16x16_bf16 v[8:11], v[154:155], v[34:35], v[8:11]
	v_pk_mul_f32 v[2:3], v[2:3], v[142:143]
	v_pk_mul_f32 v[0:1], v[0:1], v[140:141]
	v_mfma_f32_16x16x16_bf16 v[4:7], v[156:157], v[34:35], v[4:7]
	s_nop 1
	v_mfma_f32_16x16x16_bf16 v[0:3], v[158:159], v[34:35], v[0:3]
	ds_read_b128 v[112:115], v49 offset:1536
	ds_read_b64 v[144:145], v47 offset:96
	ds_read_b128 v[116:119], v49 offset:1600
	ds_read_b64 v[146:147], v47 offset:2400
	ds_read_b128 v[120:123], v49 offset:1664
	ds_read_b64 v[148:149], v47 offset:4704
	ds_read_b128 v[124:127], v49 offset:1728
	ds_read_b64 v[150:151], v47 offset:7008
	v_cvt_pk_bf16_f32 v84, v28, v29
	v_cvt_pk_bf16_f32 v85, v30, v31
	v_cvt_pk_bf16_f32 v86, v24, v25
	v_cvt_pk_bf16_f32 v87, v26, v27
	s_waitcnt lgkmcnt(8)
	v_mfma_f32_16x16x16_bf16 v[50:53], v[62:63], v[60:61], 0
	v_cvt_pk_bf16_f32 v88, v20, v21
	v_cvt_pk_bf16_f32 v89, v22, v23
	v_mfma_f32_16x16x16_bf16 v[50:53], v[68:69], v[84:85], v[50:53]
	v_mfma_f32_16x16x16_bf16 v[54:57], v[70:71], v[86:87], 0
	v_cvt_pk_bf16_f32 v90, v16, v17
	v_cvt_pk_bf16_f32 v91, v18, v19
	ds_read_b128 v[128:131], v49 offset:1792
	ds_read_b64 v[152:153], v47 offset:9312
	v_mfma_f32_16x16x16_bf16 v[50:53], v[72:73], v[88:89], v[50:53]
	v_cvt_pk_bf16_f32 v92, v12, v13
	v_cvt_pk_bf16_f32 v93, v14, v15
	ds_read_b128 v[132:135], v49 offset:1856
	ds_read_b64 v[154:155], v47 offset:11616
	v_mfma_f32_16x16x16_bf16 v[54:57], v[74:75], v[90:91], v[54:57]
	v_cvt_pk_bf16_f32 v94, v8, v9
	v_cvt_pk_bf16_f32 v95, v10, v11
	ds_read_b128 v[136:139], v49 offset:1920
	ds_read_b64 v[156:157], v47 offset:13920
	v_mfma_f32_16x16x16_bf16 v[50:53], v[76:77], v[92:93], v[50:53]
	v_cvt_pk_bf16_f32 v100, v4, v5
	v_cvt_pk_bf16_f32 v101, v6, v7
	ds_read_b128 v[140:143], v49 offset:1984
	ds_read_b64 v[158:159], v47 offset:16224
	v_mfma_f32_16x16x16_bf16 v[54:57], v[78:79], v[94:95], v[54:57]
	v_cvt_pk_bf16_f32 v102, v0, v1
	v_cvt_pk_bf16_f32 v103, v2, v3
	v_mfma_f32_16x16x16_bf16 v[50:53], v[80:81], v[100:101], v[50:53]
	s_nop 0
	v_mfma_f32_16x16x16_bf16 v[54:57], v[82:83], v[102:103], v[54:57]
	s_nop 7
	v_pk_add_f32 v[52:53], v[52:53], v[56:57]
	v_pk_add_f32 v[50:51], v[50:51], v[54:55]
	v_cvt_pk_bf16_f32 v59, v52, v53
	v_cvt_pk_bf16_f32 v58, v50, v51
	global_store_short v160, v58, s[14:15]
	global_store_short_d16_hi v161, v58, s[14:15]
	global_store_short v162, v59, s[14:15]
	global_store_short_d16_hi v163, v59, s[14:15]
	v_add_u32_e32 v160, s13, v160
	v_add_u32_e32 v161, s13, v161
	v_add_u32_e32 v162, s13, v162
	v_add_u32_e32 v163, s13, v163
	s_waitcnt lgkmcnt(0)
	v_pk_mul_f32 v[30:31], v[30:31], v[114:115]
	v_pk_mul_f32 v[28:29], v[28:29], v[112:113]
	v_pk_mul_f32 v[26:27], v[26:27], v[118:119]
	v_pk_mul_f32 v[24:25], v[24:25], v[116:117]
	v_mfma_f32_16x16x16_bf16 v[28:31], v[144:145], v[60:61], v[28:31]
	v_pk_mul_f32 v[22:23], v[22:23], v[122:123]
	v_pk_mul_f32 v[20:21], v[20:21], v[120:121]
	v_mfma_f32_16x16x16_bf16 v[24:27], v[146:147], v[60:61], v[24:27]
	v_pk_mul_f32 v[18:19], v[18:19], v[126:127]
	v_pk_mul_f32 v[16:17], v[16:17], v[124:125]
	v_mfma_f32_16x16x16_bf16 v[20:23], v[148:149], v[60:61], v[20:23]
	v_pk_mul_f32 v[14:15], v[14:15], v[130:131]
	v_pk_mul_f32 v[12:13], v[12:13], v[128:129]
	v_mfma_f32_16x16x16_bf16 v[16:19], v[150:151], v[60:61], v[16:19]
	v_pk_mul_f32 v[10:11], v[10:11], v[134:135]
	v_pk_mul_f32 v[8:9], v[8:9], v[132:133]
	v_mfma_f32_16x16x16_bf16 v[12:15], v[152:153], v[60:61], v[12:15]
	v_pk_mul_f32 v[6:7], v[6:7], v[138:139]
	v_pk_mul_f32 v[4:5], v[4:5], v[136:137]
	v_mfma_f32_16x16x16_bf16 v[8:11], v[154:155], v[60:61], v[8:11]
	v_pk_mul_f32 v[2:3], v[2:3], v[142:143]
	v_pk_mul_f32 v[0:1], v[0:1], v[140:141]
	v_mfma_f32_16x16x16_bf16 v[4:7], v[156:157], v[60:61], v[4:7]
	s_nop 1
	v_mfma_f32_16x16x16_bf16 v[0:3], v[158:159], v[60:61], v[0:3]
	s_add_i32 s0, s0, 1
	s_cmpk_lg_i32 s0, 0x81
	s_barrier
	s_cbranch_scc1 .Lhc_stage
	s_branch .LBB0_152
